# attention X phase reordered: PV groups 0,1 first from V fragments prefetched into dead score registers, then QK, then PV 2,3 with V reads issued two groups ahead
# baseline (speedup 1.0000x reference)
; #define LAS __attribute__((address_space(3)))
; __device__ __forceinline__ float qkt(f32x16& p0, f32x16& p1, const LAS char* Ks, const bf16x8* qr, int r32, int hi, int dlt, float cL, float cR, const LAS float* tabL) {
;     ...
;     for (int d0 = 0; d0 < 4; ++d0) { const int cb = d0 * 32 + hi * 16;
;         b0[d0] = *(const LAS bf16x8*)(Ks + KSWZ64(r32, cb)); b1[d0] = *(const LAS bf16x8*)(Ks + KSWZ64(32 + r32, cb)); }
;     if (dlt <= -191 || dlt >= 159) {
;         const f32x16 z = f32x16{};
;         p0 = __builtin_amdgcn_mfma_f32_32x32x16_bf16(b0[0], qr[0], z, 0, 0, 0); p1 = __builtin_amdgcn_mfma_f32_32x32x16_bf16(b1[0], qr[0], z, 0, 0, 0);
; #pragma unroll
;         for (int d0 = 1; d0 < 4; ++d0) { p0 = __builtin_amdgcn_mfma_f32_32x32x16_bf16(b0[d0], qr[d0], p0, 0, 0, 0); p1 = __builtin_amdgcn_mfma_f32_32x32x16_bf16(b1[d0], qr[d0], p1, 0, 0, 0); }
;         return dlt < 0 ? cL : cR;
.Lat_enter:
	s_setprio 1
	s_add_i32 s24, s40, 2
	s_and_b32 s24, s24, 3
	s_lshl_b32 s12, s24, 13
	s_add_i32 s12, s12, s66
	s_lshl_b32 s13, s24, 14
	s_add_i32 s13, s13, s74
	s_add_i32 m0, s12, 0x14000
	s_nop 0
	global_load_lds_dwordx4 v[204:205], off
	s_mov_b32 m0, s13
	v_lshl_add_u64 v[204:205], v[204:205], 0, s[6:7]
	global_load_lds_dwordx4 v[250:251], off
	s_add_i32 m0, s13, 0x400
	v_lshl_add_u64 v[250:251], v[250:251], 0, s[6:7]
	global_load_lds_dwordx4 v[246:247], off
	v_lshl_add_u64 v[246:247], v[246:247], 0, s[6:7]
	s_and_b32 s41, s40, 3
	s_lshl_b32 s41, s41, 13
	v_add_u32_e32 v249, s41, v239
	v_add_u32_e32 v212, s41, v240
	v_add_u32_e32 v248, s41, v241
	v_add_u32_e32 v0, s41, v242
	ds_read_b128 v[98:101], v249
	ds_read_b128 v[102:105], v249 offset:4096
	ds_read_b128 v[106:109], v212
	ds_read_b128 v[110:113], v212 offset:4096
	ds_read_b128 v[114:117], v248
	ds_read_b128 v[118:121], v248 offset:4096
	ds_read_b128 v[122:125], v0
	ds_read_b128 v[126:129], v0 offset:4096
	s_add_i32 s12, s65, 190
	s_cmp_lt_u32 s12, 349
	s_cbranch_scc1 .Lat_near_p
	s_cmp_lt_i32 s65, 0
	s_cselect_b64 vcc, -1, 0
	v_cndmask_b32_e32 v0, v224, v223, vcc
	s_waitcnt lgkmcnt(0)
	v_mfma_f32_32x32x16_bf16 v[82:97], v[98:101], v[142:145], 0
	v_mfma_f32_32x32x16_bf16 v[66:81], v[102:105], v[142:145], 0
	v_mfma_f32_32x32x16_bf16 v[82:97], v[106:109], v[138:141], v[82:97]
	v_mfma_f32_32x32x16_bf16 v[66:81], v[110:113], v[138:141], v[66:81]
	v_mfma_f32_32x32x16_bf16 v[82:97], v[114:117], v[134:137], v[82:97]
	v_mfma_f32_32x32x16_bf16 v[66:81], v[118:121], v[134:137], v[66:81]
	v_mfma_f32_32x32x16_bf16 v[82:97], v[122:125], v[130:133], v[82:97]
	v_mfma_f32_32x32x16_bf16 v[66:81], v[126:129], v[130:133], v[66:81]
	s_branch .Lat_qkd_p

; __device__ __forceinline__ void partialSM(f32x16& p0, f32x16& p1, float& m_reg, float& mn, float& alpha, float boff) {
;     ...
;     const float mnC = (boff - mn) * C;
; #pragma unroll
;     for (int r = 0; r < 16; ++r) p0[r] = fmaf(p0[r], C, mnC);
; #pragma unroll
;     for (int r = 0; r < 16; ++r) p1[r] = fmaf(p1[r], C, mnC);
; #pragma unroll
;     for (int r = 0; r < 16; ++r) p0[r] = __builtin_amdgcn_exp2f(p0[r]);
; }
; __device__ __forceinline__ void finishSM(f32x16& p0, f32x16& p1, float alpha, float& l_reg, bf16x8& pa0, bf16x8& pa1, bf16x8& pa2, bf16x8& pa3) {
; #pragma unroll
;     for (int r = 0; r < 16; ++r) p1[r] = __builtin_amdgcn_exp2f(p1[r]);
;     float ps = 0;
; #pragma unroll
;     for (int r = 0; r < 16; ++r) ps += p0[r];
; #pragma unroll
;     for (int r = 0; r < 16; ++r) ps += p1[r];
;     { auto rr = __builtin_amdgcn_permlane32_swap(__float_as_uint(ps), __float_as_uint(ps), false, false);
;       ps = __uint_as_float(rr[0]) + __uint_as_float(rr[1]); }
;     l_reg = l_reg * alpha + ps;
;     ...
;     PK4(p0, 0, pa0); PK4(p0, 8, pa1); PK4(p1, 0, pa2); PK4(p1, 8, pa3);
; template <int D0> __device__ __forceinline__ void pv_one(f32x16& od, int vb, bf16x8 pa0, bf16x8 pa1, bf16x8 pa2, bf16x8 pa3) {
;     const s16x4 l0 = tr_read<v_rd_off(D0, 0, 0)>(vb), h0 = tr_read<v_rd_off(D0, 0, 1)>(vb), l1 = tr_read<v_rd_off(D0, 1, 0)>(vb), h1 = tr_read<v_rd_off(D0, 1, 1)>(vb);
;     const s16x4 l2 = tr_read<v_rd_off(D0, 2, 0)>(vb), h2 = tr_read<v_rd_off(D0, 2, 1)>(vb), l3 = tr_read<v_rd_off(D0, 3, 0)>(vb), h3 = tr_read<v_rd_off(D0, 3, 1)>(vb);
.Lat_noresc_p:
	v_cndmask_b32_e64 v243, v249, v243, s[0:1]
	v_sub_f32_e32 v0, v0, v243
	v_mul_f32_e32 v0, 0x3e38aa3b, v0
	v_fmamk_f32 v82, v82, 0x3e38aa3b, v0
	v_fmamk_f32 v83, v83, 0x3e38aa3b, v0
	v_fmamk_f32 v84, v84, 0x3e38aa3b, v0
	v_fmamk_f32 v85, v85, 0x3e38aa3b, v0
	v_fmamk_f32 v86, v86, 0x3e38aa3b, v0
	v_fmamk_f32 v87, v87, 0x3e38aa3b, v0
	v_fmamk_f32 v88, v88, 0x3e38aa3b, v0
	v_fmamk_f32 v89, v89, 0x3e38aa3b, v0
	v_fmamk_f32 v90, v90, 0x3e38aa3b, v0
	v_fmamk_f32 v91, v91, 0x3e38aa3b, v0
	v_fmamk_f32 v92, v92, 0x3e38aa3b, v0
	v_fmamk_f32 v93, v93, 0x3e38aa3b, v0
	v_fmamk_f32 v94, v94, 0x3e38aa3b, v0
	v_fmamk_f32 v95, v95, 0x3e38aa3b, v0
	v_fmamk_f32 v96, v96, 0x3e38aa3b, v0
	v_fmamk_f32 v97, v97, 0x3e38aa3b, v0
	v_fmamk_f32 v66, v66, 0x3e38aa3b, v0
	v_fmamk_f32 v67, v67, 0x3e38aa3b, v0
	v_fmamk_f32 v68, v68, 0x3e38aa3b, v0
	v_fmamk_f32 v69, v69, 0x3e38aa3b, v0
	v_fmamk_f32 v70, v70, 0x3e38aa3b, v0
	v_fmamk_f32 v71, v71, 0x3e38aa3b, v0
	v_fmamk_f32 v72, v72, 0x3e38aa3b, v0
	v_fmamk_f32 v73, v73, 0x3e38aa3b, v0
	v_fmamk_f32 v74, v74, 0x3e38aa3b, v0
	v_fmamk_f32 v75, v75, 0x3e38aa3b, v0
	v_fmamk_f32 v76, v76, 0x3e38aa3b, v0
	v_fmamk_f32 v77, v77, 0x3e38aa3b, v0
	v_fmamk_f32 v78, v78, 0x3e38aa3b, v0
	v_fmamk_f32 v79, v79, 0x3e38aa3b, v0
	v_fmamk_f32 v80, v80, 0x3e38aa3b, v0
	v_fmamk_f32 v81, v81, 0x3e38aa3b, v0
	v_exp_f32_e32 v82, v82
	v_exp_f32_e32 v83, v83
	v_exp_f32_e32 v84, v84
	v_exp_f32_e32 v85, v85
	v_exp_f32_e32 v86, v86
	v_exp_f32_e32 v87, v87
	v_exp_f32_e32 v88, v88
	v_exp_f32_e32 v89, v89
	v_exp_f32_e32 v90, v90
	v_exp_f32_e32 v91, v91
	v_exp_f32_e32 v92, v92
	v_exp_f32_e32 v93, v93
	v_exp_f32_e32 v94, v94
	v_exp_f32_e32 v95, v95
	v_exp_f32_e32 v96, v96
	v_exp_f32_e32 v97, v97
	v_exp_f32_e32 v66, v66
	v_add_f32_e32 v244, v82, v83
	v_exp_f32_e32 v67, v67
	v_add_f32_e32 v244, v84, v244
	v_exp_f32_e32 v68, v68
	v_add_f32_e32 v244, v85, v244
	v_exp_f32_e32 v69, v69
	v_add_f32_e32 v244, v86, v244
	v_exp_f32_e32 v70, v70
	v_add_f32_e32 v244, v87, v244
	v_exp_f32_e32 v71, v71
	v_add_f32_e32 v244, v88, v244
	v_exp_f32_e32 v72, v72
	v_add_f32_e32 v244, v89, v244
	v_exp_f32_e32 v73, v73
	v_add_f32_e32 v244, v90, v244
	v_exp_f32_e32 v74, v74
	v_add_f32_e32 v244, v91, v244
	v_exp_f32_e32 v75, v75
	v_add_f32_e32 v244, v92, v244
	v_exp_f32_e32 v76, v76
	v_add_f32_e32 v244, v93, v244
	v_exp_f32_e32 v77, v77
	v_add_f32_e32 v244, v94, v244
	v_exp_f32_e32 v78, v78
	v_add_f32_e32 v244, v95, v244
	v_exp_f32_e32 v79, v79
	v_add_f32_e32 v244, v96, v244
	v_exp_f32_e32 v80, v80
	v_add_f32_e32 v244, v97, v244
	v_exp_f32_e32 v81, v81
	v_add_f32_e32 v249, v66, v67
	v_add_f32_e32 v249, v68, v249
	v_add_f32_e32 v249, v69, v249
	v_add_f32_e32 v249, v70, v249
	v_add_f32_e32 v249, v71, v249
	v_add_f32_e32 v249, v72, v249
	v_add_f32_e32 v249, v73, v249
	v_add_f32_e32 v249, v74, v249
	v_add_f32_e32 v249, v75, v249
	v_add_f32_e32 v249, v76, v249
	v_add_f32_e32 v249, v77, v249
	v_add_f32_e32 v249, v78, v249
	v_add_f32_e32 v249, v79, v249
	v_add_f32_e32 v249, v80, v249
	v_add_f32_e32 v249, v81, v249
	v_add_f32_e32 v244, v244, v249
	v_fma_f32 v238, v238, v248, v244
	v_cvt_pk_bf16_f32 v146, v82, v83
	v_cvt_pk_bf16_f32 v147, v84, v85
	v_cvt_pk_bf16_f32 v148, v86, v87
	v_cvt_pk_bf16_f32 v149, v88, v89
	v_cvt_pk_bf16_f32 v150, v90, v91
	v_cvt_pk_bf16_f32 v151, v92, v93
	v_cvt_pk_bf16_f32 v152, v94, v95
	v_cvt_pk_bf16_f32 v153, v96, v97
	v_cvt_pk_bf16_f32 v154, v66, v67
	v_cvt_pk_bf16_f32 v155, v68, v69
	v_cvt_pk_bf16_f32 v156, v70, v71
	v_cvt_pk_bf16_f32 v157, v72, v73
	v_cvt_pk_bf16_f32 v158, v74, v75
	v_cvt_pk_bf16_f32 v159, v76, v77
	v_cvt_pk_bf16_f32 v160, v78, v79
	v_cvt_pk_bf16_f32 v161, v80, v81
	s_nop 1
	v_permlane32_swap_b32_e32 v146, v148
	v_permlane32_swap_b32_e32 v147, v149
	v_permlane32_swap_b32_e32 v150, v152
	v_permlane32_swap_b32_e32 v151, v153
	v_permlane32_swap_b32_e32 v154, v156
	v_permlane32_swap_b32_e32 v155, v157
	v_permlane32_swap_b32_e32 v158, v160
	v_permlane32_swap_b32_e32 v159, v161
	s_add_i32 s40, s40, 1
	s_addk_i32 s65, 0x40
	v_add_u32_e32 v245, 0x100, v245
	s_add_i32 s54, s40, 3
	s_and_b32 s54, s54, 3
	s_lshl_b32 s54, s54, 14
	v_add_u32_e32 v244, s54, v225
	ds_read_b64_tr_b16 v[66:67], v244 offset:0x0
	ds_read_b64_tr_b16 v[68:69], v244 offset:0x800
	ds_read_b64_tr_b16 v[70:71], v244 offset:0x1000
	ds_read_b64_tr_b16 v[72:73], v244 offset:0x1800
	ds_read_b64_tr_b16 v[74:75], v244 offset:0x2000
	ds_read_b64_tr_b16 v[76:77], v244 offset:0x2800
	ds_read_b64_tr_b16 v[78:79], v244 offset:0x3000
	ds_read_b64_tr_b16 v[80:81], v244 offset:0x3800
	ds_read_b64_tr_b16 v[82:83], v244 offset:0x200
	ds_read_b64_tr_b16 v[84:85], v244 offset:0xa00
	ds_read_b64_tr_b16 v[86:87], v244 offset:0x1200
	ds_read_b64_tr_b16 v[88:89], v244 offset:0x1a00
	ds_read_b64_tr_b16 v[90:91], v244 offset:0x2200
	ds_read_b64_tr_b16 v[92:93], v244 offset:0x2a00
	ds_read_b64_tr_b16 v[94:95], v244 offset:0x3200
	ds_read_b64_tr_b16 v[96:97], v244 offset:0x3a00
	s_barrier

; #define LAS __attribute__((address_space(3)))
; #define SBAR() __builtin_amdgcn_sched_barrier(0)
; __device__ __forceinline__ float qkt(f32x16& p0, f32x16& p1, const LAS char* Ks, const bf16x8* qr, int r32, int hi, int dlt, float cL, float cR, const LAS float* tabL) {
;     ...
;     for (int d0 = 0; d0 < 4; ++d0) { const int cb = d0 * 32 + hi * 16;
;         b0[d0] = *(const LAS bf16x8*)(Ks + KSWZ64(r32, cb)); b1[d0] = *(const LAS bf16x8*)(Ks + KSWZ64(32 + r32, cb)); }
;     if (dlt <= -191 || dlt >= 159) {
;         const f32x16 z = f32x16{};
;         p0 = __builtin_amdgcn_mfma_f32_32x32x16_bf16(b0[0], qr[0], z, 0, 0, 0); p1 = __builtin_amdgcn_mfma_f32_32x32x16_bf16(b1[0], qr[0], z, 0, 0, 0);
; #pragma unroll
;         for (int d0 = 1; d0 < 4; ++d0) { p0 = __builtin_amdgcn_mfma_f32_32x32x16_bf16(b0[d0], qr[d0], p0, 0, 0, 0); p1 = __builtin_amdgcn_mfma_f32_32x32x16_bf16(b1[d0], qr[d0], p1, 0, 0, 0); }
;         return dlt < 0 ? cL : cR;
; template <int D0> __device__ __forceinline__ void pv_one(f32x16& od, int vb, bf16x8 pa0, bf16x8 pa1, bf16x8 pa2, bf16x8 pa3) {
;     const s16x4 l0 = tr_read<v_rd_off(D0, 0, 0)>(vb), h0 = tr_read<v_rd_off(D0, 0, 1)>(vb), l1 = tr_read<v_rd_off(D0, 1, 0)>(vb), h1 = tr_read<v_rd_off(D0, 1, 1)>(vb);
;     const s16x4 l2 = tr_read<v_rd_off(D0, 2, 0)>(vb), h2 = tr_read<v_rd_off(D0, 2, 1)>(vb), l3 = tr_read<v_rd_off(D0, 3, 0)>(vb), h3 = tr_read<v_rd_off(D0, 3, 1)>(vb);
;     asm volatile("s_waitcnt lgkmcnt(0)" ::: "memory"); SBAR();
;     ...
;     od = __builtin_amdgcn_mfma_f32_32x32x16_bf16(pa0, PK(l0, h0), od, 0, 0, 0);
;     od = __builtin_amdgcn_mfma_f32_32x32x16_bf16(pa1, PK(l1, h1), od, 0, 0, 0);
;     od = __builtin_amdgcn_mfma_f32_32x32x16_bf16(pa2, PK(l2, h2), od, 0, 0, 0);
;     od = __builtin_amdgcn_mfma_f32_32x32x16_bf16(pa3, PK(l3, h3), od, 0, 0, 0);
;     ...
; }
; __device__ __forceinline__ void pv_d0(f32x16* o, int vb, bf16x8 pa0, bf16x8 pa1, bf16x8 pa2, bf16x8 pa3) {
;     pv_one<0>(o[0], vb, pa0, pa1, pa2, pa3); pv_one<1>(o[1], vb, pa0, pa1, pa2, pa3); pv_one<2>(o[2], vb, pa0, pa1, pa2, pa3); pv_one<3>(o[3], vb, pa0, pa1, pa2, pa3);
.Lat_nodma_l:
	s_and_b32 s41, s40, 3
	s_lshl_b32 s41, s41, 13
	v_add_u32_e32 v249, s41, v239
	v_add_u32_e32 v212, s41, v240
	v_add_u32_e32 v248, s41, v241
	v_add_u32_e32 v0, s41, v242
	ds_read_b128 v[98:101], v249
	ds_read_b128 v[102:105], v249 offset:4096
	ds_read_b128 v[106:109], v212
	ds_read_b128 v[110:113], v212 offset:4096
	ds_read_b128 v[114:117], v248
	ds_read_b128 v[118:121], v248 offset:4096
	ds_read_b128 v[122:125], v0
	ds_read_b128 v[126:129], v0 offset:4096
	s_add_i32 s54, s40, 3
	s_and_b32 s54, s54, 3
	s_lshl_b32 s54, s54, 14
	v_add_u32_e32 v244, s54, v225
	s_waitcnt lgkmcnt(8)
	v_mfma_f32_32x32x16_bf16 v[50:65], v[146:149], v[66:69], v[50:65]
	ds_read_b64_tr_b16 v[162:163], v244 offset:0x400
	ds_read_b64_tr_b16 v[164:165], v244 offset:0xc00
	v_mfma_f32_32x32x16_bf16 v[50:65], v[150:153], v[70:73], v[50:65]
	ds_read_b64_tr_b16 v[166:167], v244 offset:0x1400
	ds_read_b64_tr_b16 v[168:169], v244 offset:0x1c00
	v_mfma_f32_32x32x16_bf16 v[50:65], v[154:157], v[74:77], v[50:65]
	ds_read_b64_tr_b16 v[170:171], v244 offset:0x2400
	ds_read_b64_tr_b16 v[172:173], v244 offset:0x2c00
	v_mfma_f32_32x32x16_bf16 v[50:65], v[158:161], v[78:81], v[50:65]
	ds_read_b64_tr_b16 v[174:175], v244 offset:0x3400
	ds_read_b64_tr_b16 v[176:177], v244 offset:0x3c00
	v_mfma_f32_32x32x16_bf16 v[34:49], v[146:149], v[82:85], v[34:49]
	v_mfma_f32_32x32x16_bf16 v[34:49], v[150:153], v[86:89], v[34:49]
	v_mfma_f32_32x32x16_bf16 v[34:49], v[154:157], v[90:93], v[34:49]
	v_mfma_f32_32x32x16_bf16 v[34:49], v[158:161], v[94:97], v[34:49]
	s_add_i32 s12, s65, 190
	s_cmp_lt_u32 s12, 349
	s_cbranch_scc1 .Lat_near_l
	s_cmp_lt_i32 s65, 0
	s_cselect_b64 vcc, -1, 0
	v_cndmask_b32_e32 v0, v224, v223, vcc
	s_waitcnt lgkmcnt(8)
	v_mfma_f32_32x32x16_bf16 v[82:97], v[98:101], v[142:145], 0
	v_mfma_f32_32x32x16_bf16 v[66:81], v[102:105], v[142:145], 0
	v_mfma_f32_32x32x16_bf16 v[82:97], v[106:109], v[138:141], v[82:97]
	v_mfma_f32_32x32x16_bf16 v[66:81], v[110:113], v[138:141], v[66:81]
	v_mfma_f32_32x32x16_bf16 v[82:97], v[114:117], v[134:137], v[82:97]
	v_mfma_f32_32x32x16_bf16 v[66:81], v[118:121], v[134:137], v[66:81]
	v_mfma_f32_32x32x16_bf16 v[82:97], v[122:125], v[130:133], v[82:97]
	v_mfma_f32_32x32x16_bf16 v[66:81], v[126:129], v[130:133], v[66:81]
	s_branch .Lat_qkd_l

; #define SBAR() __builtin_amdgcn_sched_barrier(0)
; template <int D0> __device__ __forceinline__ void pv_one(f32x16& od, int vb, bf16x8 pa0, bf16x8 pa1, bf16x8 pa2, bf16x8 pa3) {
;     const s16x4 l0 = tr_read<v_rd_off(D0, 0, 0)>(vb), h0 = tr_read<v_rd_off(D0, 0, 1)>(vb), l1 = tr_read<v_rd_off(D0, 1, 0)>(vb), h1 = tr_read<v_rd_off(D0, 1, 1)>(vb);
;     const s16x4 l2 = tr_read<v_rd_off(D0, 2, 0)>(vb), h2 = tr_read<v_rd_off(D0, 2, 1)>(vb), l3 = tr_read<v_rd_off(D0, 3, 0)>(vb), h3 = tr_read<v_rd_off(D0, 3, 1)>(vb);
;     asm volatile("s_waitcnt lgkmcnt(0)" ::: "memory"); SBAR();
;     ...
;     od = __builtin_amdgcn_mfma_f32_32x32x16_bf16(pa0, PK(l0, h0), od, 0, 0, 0);
;     od = __builtin_amdgcn_mfma_f32_32x32x16_bf16(pa1, PK(l1, h1), od, 0, 0, 0);
;     od = __builtin_amdgcn_mfma_f32_32x32x16_bf16(pa2, PK(l2, h2), od, 0, 0, 0);
;     od = __builtin_amdgcn_mfma_f32_32x32x16_bf16(pa3, PK(l3, h3), od, 0, 0, 0);
;     ...
; }
; __device__ __forceinline__ void pv_d0(f32x16* o, int vb, bf16x8 pa0, bf16x8 pa1, bf16x8 pa2, bf16x8 pa3) {
;     pv_one<0>(o[0], vb, pa0, pa1, pa2, pa3); pv_one<1>(o[1], vb, pa0, pa1, pa2, pa3); pv_one<2>(o[2], vb, pa0, pa1, pa2, pa3); pv_one<3>(o[3], vb, pa0, pa1, pa2, pa3);
.Lat_qkd_l:
	ds_read_b64_tr_b16 v[98:99], v244 offset:0x600
	ds_read_b64_tr_b16 v[100:101], v244 offset:0xe00
	ds_read_b64_tr_b16 v[102:103], v244 offset:0x1600
	ds_read_b64_tr_b16 v[104:105], v244 offset:0x1e00
	ds_read_b64_tr_b16 v[106:107], v244 offset:0x2600
	ds_read_b64_tr_b16 v[108:109], v244 offset:0x2e00
	ds_read_b64_tr_b16 v[110:111], v244 offset:0x3600
	ds_read_b64_tr_b16 v[112:113], v244 offset:0x3e00
	s_waitcnt lgkmcnt(8)
	v_mfma_f32_32x32x16_bf16 v[18:33], v[146:149], v[162:165], v[18:33]
	v_mfma_f32_32x32x16_bf16 v[18:33], v[150:153], v[166:169], v[18:33]
	v_mfma_f32_32x32x16_bf16 v[18:33], v[154:157], v[170:173], v[18:33]
	v_mfma_f32_32x32x16_bf16 v[18:33], v[158:161], v[174:177], v[18:33]
	s_waitcnt lgkmcnt(0)
	v_mfma_f32_32x32x16_bf16 v[2:17], v[146:149], v[98:101], v[2:17]
	v_mfma_f32_32x32x16_bf16 v[2:17], v[150:153], v[102:105], v[2:17]
	v_mfma_f32_32x32x16_bf16 v[2:17], v[154:157], v[106:109], v[2:17]
	v_mfma_f32_32x32x16_bf16 v[2:17], v[158:161], v[110:113], v[2:17]
	s_setprio 0
	s_cmp_gt_u32 s40, 61
	s_cbranch_scc1 .Lat_w0_l
	s_waitcnt vmcnt(3)
	s_branch .Lat_wd_l

; __device__ __forceinline__ void partialSM(f32x16& p0, f32x16& p1, float& m_reg, float& mn, float& alpha, float boff) {
;     ...
;     const float mnC = (boff - mn) * C;
; #pragma unroll
;     for (int r = 0; r < 16; ++r) p0[r] = fmaf(p0[r], C, mnC);
; #pragma unroll
;     for (int r = 0; r < 16; ++r) p1[r] = fmaf(p1[r], C, mnC);
; #pragma unroll
;     for (int r = 0; r < 16; ++r) p0[r] = __builtin_amdgcn_exp2f(p0[r]);
; }
; __device__ __forceinline__ void finishSM(f32x16& p0, f32x16& p1, float alpha, float& l_reg, bf16x8& pa0, bf16x8& pa1, bf16x8& pa2, bf16x8& pa3) {
; #pragma unroll
;     for (int r = 0; r < 16; ++r) p1[r] = __builtin_amdgcn_exp2f(p1[r]);
;     float ps = 0;
; #pragma unroll
;     for (int r = 0; r < 16; ++r) ps += p0[r];
; #pragma unroll
;     for (int r = 0; r < 16; ++r) ps += p1[r];
;     { auto rr = __builtin_amdgcn_permlane32_swap(__float_as_uint(ps), __float_as_uint(ps), false, false);
;       ps = __uint_as_float(rr[0]) + __uint_as_float(rr[1]); }
;     l_reg = l_reg * alpha + ps;
;     ...
;     PK4(p0, 0, pa0); PK4(p0, 8, pa1); PK4(p1, 0, pa2); PK4(p1, 8, pa3);
; template <int D0> __device__ __forceinline__ void pv_one(f32x16& od, int vb, bf16x8 pa0, bf16x8 pa1, bf16x8 pa2, bf16x8 pa3) {
;     const s16x4 l0 = tr_read<v_rd_off(D0, 0, 0)>(vb), h0 = tr_read<v_rd_off(D0, 0, 1)>(vb), l1 = tr_read<v_rd_off(D0, 1, 0)>(vb), h1 = tr_read<v_rd_off(D0, 1, 1)>(vb);
;     const s16x4 l2 = tr_read<v_rd_off(D0, 2, 0)>(vb), h2 = tr_read<v_rd_off(D0, 2, 1)>(vb), l3 = tr_read<v_rd_off(D0, 3, 0)>(vb), h3 = tr_read<v_rd_off(D0, 3, 1)>(vb);
.Lat_noresc_l:
	v_cndmask_b32_e64 v243, v249, v243, s[0:1]
	v_sub_f32_e32 v0, v0, v243
	v_mul_f32_e32 v0, 0x3e38aa3b, v0
	v_fmamk_f32 v82, v82, 0x3e38aa3b, v0
	v_fmamk_f32 v83, v83, 0x3e38aa3b, v0
	v_fmamk_f32 v84, v84, 0x3e38aa3b, v0
	v_fmamk_f32 v85, v85, 0x3e38aa3b, v0
	v_fmamk_f32 v86, v86, 0x3e38aa3b, v0
	v_fmamk_f32 v87, v87, 0x3e38aa3b, v0
	v_fmamk_f32 v88, v88, 0x3e38aa3b, v0
	v_fmamk_f32 v89, v89, 0x3e38aa3b, v0
	v_fmamk_f32 v90, v90, 0x3e38aa3b, v0
	v_fmamk_f32 v91, v91, 0x3e38aa3b, v0
	v_fmamk_f32 v92, v92, 0x3e38aa3b, v0
	v_fmamk_f32 v93, v93, 0x3e38aa3b, v0
	v_fmamk_f32 v94, v94, 0x3e38aa3b, v0
	v_fmamk_f32 v95, v95, 0x3e38aa3b, v0
	v_fmamk_f32 v96, v96, 0x3e38aa3b, v0
	v_fmamk_f32 v97, v97, 0x3e38aa3b, v0
	v_fmamk_f32 v66, v66, 0x3e38aa3b, v0
	v_fmamk_f32 v67, v67, 0x3e38aa3b, v0
	v_fmamk_f32 v68, v68, 0x3e38aa3b, v0
	v_fmamk_f32 v69, v69, 0x3e38aa3b, v0
	v_fmamk_f32 v70, v70, 0x3e38aa3b, v0
	v_fmamk_f32 v71, v71, 0x3e38aa3b, v0
	v_fmamk_f32 v72, v72, 0x3e38aa3b, v0
	v_fmamk_f32 v73, v73, 0x3e38aa3b, v0
	v_fmamk_f32 v74, v74, 0x3e38aa3b, v0
	v_fmamk_f32 v75, v75, 0x3e38aa3b, v0
	v_fmamk_f32 v76, v76, 0x3e38aa3b, v0
	v_fmamk_f32 v77, v77, 0x3e38aa3b, v0
	v_fmamk_f32 v78, v78, 0x3e38aa3b, v0
	v_fmamk_f32 v79, v79, 0x3e38aa3b, v0
	v_fmamk_f32 v80, v80, 0x3e38aa3b, v0
	v_fmamk_f32 v81, v81, 0x3e38aa3b, v0
	v_exp_f32_e32 v82, v82
	v_exp_f32_e32 v83, v83
	v_exp_f32_e32 v84, v84
	v_exp_f32_e32 v85, v85
	v_exp_f32_e32 v86, v86
	v_exp_f32_e32 v87, v87
	v_exp_f32_e32 v88, v88
	v_exp_f32_e32 v89, v89
	v_exp_f32_e32 v90, v90
	v_exp_f32_e32 v91, v91
	v_exp_f32_e32 v92, v92
	v_exp_f32_e32 v93, v93
	v_exp_f32_e32 v94, v94
	v_exp_f32_e32 v95, v95
	v_exp_f32_e32 v96, v96
	v_exp_f32_e32 v97, v97
	v_exp_f32_e32 v66, v66
	v_add_f32_e32 v244, v82, v83
	v_exp_f32_e32 v67, v67
	v_add_f32_e32 v244, v84, v244
	v_exp_f32_e32 v68, v68
	v_add_f32_e32 v244, v85, v244
	v_exp_f32_e32 v69, v69
	v_add_f32_e32 v244, v86, v244
	v_exp_f32_e32 v70, v70
	v_add_f32_e32 v244, v87, v244
	v_exp_f32_e32 v71, v71
	v_add_f32_e32 v244, v88, v244
	v_exp_f32_e32 v72, v72
	v_add_f32_e32 v244, v89, v244
	v_exp_f32_e32 v73, v73
	v_add_f32_e32 v244, v90, v244
	v_exp_f32_e32 v74, v74
	v_add_f32_e32 v244, v91, v244
	v_exp_f32_e32 v75, v75
	v_add_f32_e32 v244, v92, v244
	v_exp_f32_e32 v76, v76
	v_add_f32_e32 v244, v93, v244
	v_exp_f32_e32 v77, v77
	v_add_f32_e32 v244, v94, v244
	v_exp_f32_e32 v78, v78
	v_add_f32_e32 v244, v95, v244
	v_exp_f32_e32 v79, v79
	v_add_f32_e32 v244, v96, v244
	v_exp_f32_e32 v80, v80
	v_add_f32_e32 v244, v97, v244
	v_exp_f32_e32 v81, v81
	v_add_f32_e32 v249, v66, v67
	v_add_f32_e32 v249, v68, v249
	v_add_f32_e32 v249, v69, v249
	v_add_f32_e32 v249, v70, v249
	v_add_f32_e32 v249, v71, v249
	v_add_f32_e32 v249, v72, v249
	v_add_f32_e32 v249, v73, v249
	v_add_f32_e32 v249, v74, v249
	v_add_f32_e32 v249, v75, v249
	v_add_f32_e32 v249, v76, v249
	v_add_f32_e32 v249, v77, v249
	v_add_f32_e32 v249, v78, v249
	v_add_f32_e32 v249, v79, v249
	v_add_f32_e32 v249, v80, v249
	v_add_f32_e32 v249, v81, v249
	v_add_f32_e32 v244, v244, v249
	v_fma_f32 v238, v238, v248, v244
	v_cvt_pk_bf16_f32 v146, v82, v83
	v_cvt_pk_bf16_f32 v147, v84, v85
	v_cvt_pk_bf16_f32 v148, v86, v87
	v_cvt_pk_bf16_f32 v149, v88, v89
	v_cvt_pk_bf16_f32 v150, v90, v91
	v_cvt_pk_bf16_f32 v151, v92, v93
	v_cvt_pk_bf16_f32 v152, v94, v95
	v_cvt_pk_bf16_f32 v153, v96, v97
	v_cvt_pk_bf16_f32 v154, v66, v67
	v_cvt_pk_bf16_f32 v155, v68, v69
	v_cvt_pk_bf16_f32 v156, v70, v71
	v_cvt_pk_bf16_f32 v157, v72, v73
	v_cvt_pk_bf16_f32 v158, v74, v75
	v_cvt_pk_bf16_f32 v159, v76, v77
	v_cvt_pk_bf16_f32 v160, v78, v79
	v_cvt_pk_bf16_f32 v161, v80, v81
	s_nop 1
	v_permlane32_swap_b32_e32 v146, v148
	v_permlane32_swap_b32_e32 v147, v149
	v_permlane32_swap_b32_e32 v150, v152
	v_permlane32_swap_b32_e32 v151, v153
	v_permlane32_swap_b32_e32 v154, v156
	v_permlane32_swap_b32_e32 v155, v157
	v_permlane32_swap_b32_e32 v158, v160
	v_permlane32_swap_b32_e32 v159, v161
	s_add_i32 s40, s40, 1
	s_addk_i32 s65, 0x40
	v_add_u32_e32 v245, 0x100, v245
	s_add_i32 s54, s40, 3
	s_and_b32 s54, s54, 3
	s_lshl_b32 s54, s54, 14
	v_add_u32_e32 v244, s54, v225
	ds_read_b64_tr_b16 v[66:67], v244 offset:0x0
	ds_read_b64_tr_b16 v[68:69], v244 offset:0x800
	ds_read_b64_tr_b16 v[70:71], v244 offset:0x1000
	ds_read_b64_tr_b16 v[72:73], v244 offset:0x1800
	ds_read_b64_tr_b16 v[74:75], v244 offset:0x2000
	ds_read_b64_tr_b16 v[76:77], v244 offset:0x2800
	ds_read_b64_tr_b16 v[78:79], v244 offset:0x3000
	ds_read_b64_tr_b16 v[80:81], v244 offset:0x3800
	ds_read_b64_tr_b16 v[82:83], v244 offset:0x200
	ds_read_b64_tr_b16 v[84:85], v244 offset:0xa00
	ds_read_b64_tr_b16 v[86:87], v244 offset:0x1200
	ds_read_b64_tr_b16 v[88:89], v244 offset:0x1a00
	ds_read_b64_tr_b16 v[90:91], v244 offset:0x2200
	ds_read_b64_tr_b16 v[92:93], v244 offset:0x2a00
	ds_read_b64_tr_b16 v[94:95], v244 offset:0x3200
	ds_read_b64_tr_b16 v[96:97], v244 offset:0x3a00
	s_barrier
; #define SBAR() __builtin_amdgcn_sched_barrier(0)
; #define RESC(a) do { if (__any((a) < 1.f)) { if (hi == 0) al_l[r32] = (a); asm volatile("s_waitcnt lgkmcnt(0)" ::: "memory"); \
;         _Pragma("unroll") for (int d = 0; d < 4; ++d) _Pragma("unroll") for (int r = 0; r < 16; ++r) o[d][r] *= al_l[crow(r, hi)]; } } while (0)
; template <int D0> __device__ __forceinline__ void pv_one(f32x16& od, int vb, bf16x8 pa0, bf16x8 pa1, bf16x8 pa2, bf16x8 pa3) {
;     const s16x4 l0 = tr_read<v_rd_off(D0, 0, 0)>(vb), h0 = tr_read<v_rd_off(D0, 0, 1)>(vb), l1 = tr_read<v_rd_off(D0, 1, 0)>(vb), h1 = tr_read<v_rd_off(D0, 1, 1)>(vb);
;     const s16x4 l2 = tr_read<v_rd_off(D0, 2, 0)>(vb), h2 = tr_read<v_rd_off(D0, 2, 1)>(vb), l3 = tr_read<v_rd_off(D0, 3, 0)>(vb), h3 = tr_read<v_rd_off(D0, 3, 1)>(vb);
;     asm volatile("s_waitcnt lgkmcnt(0)" ::: "memory"); SBAR();
;     ...
;     od = __builtin_amdgcn_mfma_f32_32x32x16_bf16(pa0, PK(l0, h0), od, 0, 0, 0);
;     od = __builtin_amdgcn_mfma_f32_32x32x16_bf16(pa1, PK(l1, h1), od, 0, 0, 0);
;     od = __builtin_amdgcn_mfma_f32_32x32x16_bf16(pa2, PK(l2, h2), od, 0, 0, 0);
;     od = __builtin_amdgcn_mfma_f32_32x32x16_bf16(pa3, PK(l3, h3), od, 0, 0, 0);
;     ...
; }
; __device__ __forceinline__ void pv_d0(f32x16* o, int vb, bf16x8 pa0, bf16x8 pa1, bf16x8 pa2, bf16x8 pa3) {
;     pv_one<0>(o[0], vb, pa0, pa1, pa2, pa3); pv_one<1>(o[1], vb, pa0, pa1, pa2, pa3); pv_one<2>(o[2], vb, pa0, pa1, pa2, pa3); pv_one<3>(o[3], vb, pa0, pa1, pa2, pa3);
; __device__ __forceinline__ void attn_unit(int b, int h, int qb, const bf16_t* __restrict__ proj, const float* __restrict__ btab, float lam, float outscale,
;                                           const float* __restrict__ gain, float* o1scr, bf16_t* merged, LAS char* lds) {
;     ...
;         SBAR(); bo = qkt(pB0, pB1, K_lds + bc * SHM_K, qr, r32, hi, (NT - 1) * 64 - qw, cL, cR, tabL);
;         finishSM(pA0, pA1, alA, l_reg, pa0, pa1, pa2, pa3); SBAR();
;         pv_d0(o, vb0 + bp * SHM_V, pa0, pa1, pa2, pa3); partialSM(pB0, pB1, m_reg, mnB, alB, bo);
;         RESC(alB);
;         finishSM(pB0, pB1, alB, l_reg, pa0, pa1, pa2, pa3); SBAR();
;         pv_d0(o, vb0 + bc * SHM_V, pa0, pa1, pa2, pa3);
	s_cmp_lt_u32 s40, 64
	s_cbranch_scc1 .Lat_loop
	s_setprio 1
	s_add_i32 s54, s40, 3
	s_and_b32 s54, s54, 3
	s_lshl_b32 s54, s54, 14
	v_add_u32_e32 v244, s54, v225
	s_waitcnt lgkmcnt(0)
	v_mfma_f32_32x32x16_bf16 v[50:65], v[146:149], v[66:69], v[50:65]
	ds_read_b64_tr_b16 v[162:163], v244 offset:0x400
	ds_read_b64_tr_b16 v[164:165], v244 offset:0xc00
	v_mfma_f32_32x32x16_bf16 v[50:65], v[150:153], v[70:73], v[50:65]
	ds_read_b64_tr_b16 v[166:167], v244 offset:0x1400
	ds_read_b64_tr_b16 v[168:169], v244 offset:0x1c00
	v_mfma_f32_32x32x16_bf16 v[50:65], v[154:157], v[74:77], v[50:65]
	ds_read_b64_tr_b16 v[170:171], v244 offset:0x2400
	ds_read_b64_tr_b16 v[172:173], v244 offset:0x2c00
	v_mfma_f32_32x32x16_bf16 v[50:65], v[158:161], v[78:81], v[50:65]
	ds_read_b64_tr_b16 v[174:175], v244 offset:0x3400
	ds_read_b64_tr_b16 v[176:177], v244 offset:0x3c00
	ds_read_b64_tr_b16 v[98:99], v244 offset:0x600
	ds_read_b64_tr_b16 v[100:101], v244 offset:0xe00
	ds_read_b64_tr_b16 v[102:103], v244 offset:0x1600
	ds_read_b64_tr_b16 v[104:105], v244 offset:0x1e00
	ds_read_b64_tr_b16 v[106:107], v244 offset:0x2600
	ds_read_b64_tr_b16 v[108:109], v244 offset:0x2e00
	ds_read_b64_tr_b16 v[110:111], v244 offset:0x3600
	ds_read_b64_tr_b16 v[112:113], v244 offset:0x3e00
	v_mfma_f32_32x32x16_bf16 v[34:49], v[146:149], v[82:85], v[34:49]
	v_mfma_f32_32x32x16_bf16 v[34:49], v[150:153], v[86:89], v[34:49]
	v_mfma_f32_32x32x16_bf16 v[34:49], v[154:157], v[90:93], v[34:49]
	v_mfma_f32_32x32x16_bf16 v[34:49], v[158:161], v[94:97], v[34:49]
	s_waitcnt lgkmcnt(8)
	v_mfma_f32_32x32x16_bf16 v[18:33], v[146:149], v[162:165], v[18:33]
	v_mfma_f32_32x32x16_bf16 v[18:33], v[150:153], v[166:169], v[18:33]
	v_mfma_f32_32x32x16_bf16 v[18:33], v[154:157], v[170:173], v[18:33]
	v_mfma_f32_32x32x16_bf16 v[18:33], v[158:161], v[174:177], v[18:33]
	s_waitcnt lgkmcnt(0)
	v_mfma_f32_32x32x16_bf16 v[2:17], v[146:149], v[98:101], v[2:17]
	v_mfma_f32_32x32x16_bf16 v[2:17], v[150:153], v[102:105], v[2:17]
	v_mfma_f32_32x32x16_bf16 v[2:17], v[154:157], v[106:109], v[2:17]
	v_mfma_f32_32x32x16_bf16 v[2:17], v[158:161], v[110:113], v[2:17]
	s_setprio 0
	s_cmp_lg_u32 s67, 0
	s_cbranch_scc1 .Lat_fin
	s_barrier
